# v91 + nt on the merge phase's input loads (all dead after the phase)
# speedup vs baseline: 1.0118x; 1.0012x over previous
.LBB0_355:
	v_readlane_b32 s0, v252, 10
	v_ashrrev_i32_e32 v196, 7, v169
	v_readlane_b32 s1, v252, 11
	v_ashrrev_i32_e32 v197, 31, v196
	s_movk_i32 s4, 0x1a00
	v_mov_b64_e32 v[142:143], s[0:1]
	v_lshlrev_b64 v[140:141], 11, v[196:197]
	v_mad_i64_i32 v[142:143], s[0:1], v196, s4, v[142:143]
	v_lshlrev_b32_e32 v184, 1, v168
	v_lshlrev_b64 v[144:145], 9, v[196:197]
	v_lshl_add_u64 v[142:143], v[142:143], 0, v[184:185]
	s_movk_i32 s0, 0x1000
	v_lshl_add_u64 v[144:145], v[172:173], 0, v[144:145]
	v_lshl_add_u64 v[146:147], v[188:189], 0, v[140:141]
	v_lshl_add_u64 v[132:133], v[186:187], 0, v[140:141]
	v_lshl_add_u64 v[136:137], v[170:171], 0, v[140:141]
	v_add_co_u32_e32 v142, vcc, s0, v142
	v_cndmask_b32_e64 v145, v147, v145, s[38:39]
	v_cndmask_b32_e64 v144, v146, v144, s[38:39]
	global_load_dwordx4 v[132:135], v[132:133], off nt
	s_nop 0
	global_load_dwordx4 v[136:139], v[136:137], off nt
	v_addc_co_u32_e32 v143, vcc, 0, v143, vcc
	global_load_dwordx4 v[148:151], v[144:145], off nt
	v_lshl_add_u64 v[144:145], v[174:175], 0, v[140:141]
	v_mad_i64_i32 v[152:153], s[0:1], v196, s4, v[176:177]
	v_lshlrev_b64 v[154:155], 6, v[196:197]
	global_load_dwordx4 v[140:143], v[142:143], off nt
	s_nop 0
	global_load_dwordx4 v[144:147], v[144:145], off nt
	v_lshl_add_u64 v[156:157], v[190:191], 0, v[154:155]
	global_load_dwordx4 v[152:155], v[152:153], off nt
	s_nop 0
	global_load_dword v198, v[156:157], off
	s_movk_i32 s73, 0x1a00
	v_cmp_gt_i32_e64 s[0:1], s70, v196
	s_and_saveexec_b64 s[4:5], s[0:1]
	s_xor_b64 s[4:5], exec, s[4:5]
	s_cbranch_execz .LBB0_361
	s_mov_b32 s6, 0xfe03f81
	v_mul_hi_i32 v156, v196, s6
	v_lshrrev_b32_e32 v157, 31, v156
	v_ashrrev_i32_e32 v156, 7, v156
	v_add_u32_e32 v156, v156, v157
	v_mul_lo_u32 v156, v156, s81
	v_sub_u32_e32 v156, v196, v156
	v_mov_b32_e32 v159, 0
	v_cmp_lt_i32_e32 vcc, 0, v156
	v_mov_b32_e32 v160, 0
	v_mov_b32_e32 v161, 0
	v_mov_b32_e32 v162, 0
	v_mov_b32_e32 v163, 0
	v_mov_b32_e32 v164, 0
	v_mov_b32_e32 v165, 0
	v_mov_b32_e32 v166, 0
	v_mov_b32_e32 v167, 0
	s_and_saveexec_b64 s[6:7], vcc
	s_cbranch_execz .LBB0_358
	v_add_u32_e32 v157, -1, v196
	s_movk_i32 s10, 0x1a00
	v_mad_i64_i32 v[160:161], s[8:9], v157, s10, v[176:177]
	v_readlane_b32 s8, v252, 10
	v_readlane_b32 s9, v252, 11
	s_nop 1
	v_mov_b64_e32 v[162:163], s[8:9]
	v_mad_i64_i32 v[162:163], s[8:9], v157, s10, v[162:163]
	v_lshl_add_u64 v[162:163], v[162:163], 0, v[184:185]
	v_add_co_u32_e32 v164, vcc, 0x1000, v162
	s_nop 1
	v_addc_co_u32_e32 v165, vcc, 0, v163, vcc
	global_load_dwordx4 v[160:163], v[160:161], off nt
	s_nop 0
	global_load_dwordx4 v[164:167], v[164:165], off nt
.LBB0_358:
	s_or_b64 exec, exec, s[6:7]
	v_cmp_lt_i32_e32 vcc, 1, v156
	v_mov_b32_e32 v158, 0
	v_mov_b32_e32 v157, 0
	v_mov_b32_e32 v156, 0
	s_and_saveexec_b64 s[6:7], vcc
	s_cbranch_execz .LBB0_360
	v_add_u32_e32 v156, -2, v196
	v_mad_i64_i32 v[156:157], s[8:9], v156, s73, v[176:177]
	global_load_dwordx4 v[156:159], v[156:157], off nt

.LBB0_361:
	s_andn2_saveexec_b64 s[4:5], s[4:5]
	s_cbranch_execz .LBB0_363
	v_add_u32_e32 v70, 0xffffbf80, v196
	v_lshlrev_b32_e32 v64, 1, v70
	v_or_b32_e32 v66, 1, v64
	v_mov_b32_e32 v67, v185
	v_mov_b32_e32 v65, v185
	v_lshlrev_b64 v[66:67], 12, v[66:67]
	v_lshlrev_b64 v[64:65], 12, v[64:65]
	s_movk_i32 s6, 0x3400
	v_lshl_add_u64 v[68:69], v[178:179], 0, v[66:67]
	v_lshl_add_u64 v[96:97], v[178:179], 0, v[64:65]
	v_mad_u64_u32 v[116:117], s[6:7], v70, s6, v[180:181]
	global_load_dwordx4 v[64:67], v[68:69], off offset:16 nt
	s_nop 0
	global_load_dwordx4 v[68:71], v[68:69], off nt
	s_nop 0
	global_load_dwordx4 v[92:95], v[96:97], off offset:16 nt
	s_nop 0
	global_load_dwordx4 v[96:99], v[96:97], off nt
	s_nop 0
	global_load_dwordx4 v[112:115], v[116:117], off offset:16 nt
	s_nop 0
	global_load_dwordx4 v[116:119], v[116:117], off nt
	s_waitcnt vmcnt(6)
	v_mov_b32_e32 v156, 0
	v_mov_b32_e32 v157, 0
	v_mov_b32_e32 v158, 0
	v_mov_b32_e32 v159, 0
	v_mov_b32_e32 v160, 0
	v_mov_b32_e32 v161, 0
	v_mov_b32_e32 v162, 0
	v_mov_b32_e32 v163, 0
	v_mov_b32_e32 v164, 0
	v_mov_b32_e32 v165, 0
	v_mov_b32_e32 v166, 0
	v_mov_b32_e32 v167, 0
.LBB0_363:
	s_or_b64 exec, exec, s[4:5]
	v_add_u32_e32 v193, s79, v169
	s_mov_b32 s4, 0x208000
	v_cmp_gt_i32_e64 s[40:41], s4, v193
	v_ashrrev_i32_e32 v194, 7, v193
	s_and_saveexec_b64 s[4:5], s[40:41]
	s_cbranch_execz .LBB0_373
	v_readlane_b32 s6, v252, 10
	v_readlane_b32 s7, v252, 11
	s_movk_i32 s8, 0x1a00
	v_ashrrev_i32_e32 v195, 31, v194
	v_mov_b64_e32 v[80:81], s[6:7]
	v_mad_i64_i32 v[80:81], s[6:7], v194, s8, v[80:81]
	v_lshl_add_u64 v[80:81], v[80:81], 0, v[184:185]
	v_add_co_u32_e32 v86, vcc, 0x1000, v80
	v_lshlrev_b64 v[84:85], 11, v[194:195]
	s_nop 0
	v_addc_co_u32_e32 v87, vcc, 0, v81, vcc
	v_lshlrev_b64 v[80:81], 9, v[194:195]
	v_lshl_add_u64 v[80:81], v[172:173], 0, v[80:81]
	v_lshl_add_u64 v[82:83], v[188:189], 0, v[84:85]
	v_lshl_add_u64 v[48:49], v[186:187], 0, v[84:85]
	v_lshl_add_u64 v[52:53], v[170:171], 0, v[84:85]
	v_cndmask_b32_e64 v81, v83, v81, s[38:39]
	v_cndmask_b32_e64 v80, v82, v80, s[38:39]
	v_lshl_add_u64 v[88:89], v[174:175], 0, v[84:85]
	v_mad_i64_i32 v[100:101], s[6:7], v194, s8, v[176:177]
	v_lshlrev_b64 v[102:103], 6, v[194:195]
	global_load_dwordx4 v[48:51], v[48:49], off nt
	s_nop 0
	global_load_dwordx4 v[52:55], v[52:53], off nt
	v_lshl_add_u64 v[120:121], v[190:191], 0, v[102:103]
	global_load_dwordx4 v[80:83], v[80:81], off nt
	s_nop 0
	global_load_dwordx4 v[84:87], v[86:87], off nt
	s_nop 0
	global_load_dwordx4 v[88:91], v[88:89], off nt
	s_nop 0
	global_load_dwordx4 v[100:103], v[100:101], off nt
	s_nop 0
	global_load_dword v192, v[120:121], off
	v_cmp_gt_i32_e32 vcc, s70, v194
	s_and_saveexec_b64 s[6:7], vcc
	s_xor_b64 s[6:7], exec, s[6:7]
	s_cbranch_execz .LBB0_370
	s_mov_b32 s8, 0xfe03f81
	v_mul_hi_i32 v120, v194, s8
	v_lshrrev_b32_e32 v121, 31, v120
	v_ashrrev_i32_e32 v120, 7, v120
	v_add_u32_e32 v120, v120, v121
	v_mul_lo_u32 v120, v120, s81
	v_sub_u32_e32 v120, v194, v120
	v_mov_b32_e32 v123, 0
	v_cmp_lt_i32_e32 vcc, 0, v120
	v_mov_b32_e32 v128, 0
	v_mov_b32_e32 v129, 0
	v_mov_b32_e32 v130, 0
	v_mov_b32_e32 v131, 0
	v_mov_b32_e32 v124, 0
	v_mov_b32_e32 v125, 0
	v_mov_b32_e32 v126, 0
	v_mov_b32_e32 v127, 0
	s_and_saveexec_b64 s[8:9], vcc
	s_cbranch_execz .LBB0_367
	v_add_u32_e32 v121, -1, v194
	s_movk_i32 s12, 0x1a00
	v_mad_i64_i32 v[124:125], s[10:11], v121, s12, v[176:177]
	v_readlane_b32 s10, v252, 10
	v_readlane_b32 s11, v252, 11
	s_nop 1
	v_mov_b64_e32 v[126:127], s[10:11]
	v_mad_i64_i32 v[126:127], s[10:11], v121, s12, v[126:127]
	v_lshl_add_u64 v[126:127], v[126:127], 0, v[184:185]
	v_add_co_u32_e32 v128, vcc, 0x1000, v126
	s_nop 1
	v_addc_co_u32_e32 v129, vcc, 0, v127, vcc
	global_load_dwordx4 v[124:127], v[124:125], off nt
	s_nop 0
	global_load_dwordx4 v[128:131], v[128:129], off nt
.LBB0_367:
	s_or_b64 exec, exec, s[8:9]
	v_cmp_lt_i32_e32 vcc, 1, v120
	v_mov_b32_e32 v122, 0
	v_mov_b32_e32 v121, 0
	v_mov_b32_e32 v120, 0
	s_and_saveexec_b64 s[8:9], vcc
	s_cbranch_execz .LBB0_369
	v_add_u32_e32 v120, -2, v194
	v_mad_i64_i32 v[120:121], s[10:11], v120, s73, v[176:177]
	global_load_dwordx4 v[120:123], v[120:121], off nt

.LBB0_370:
	s_andn2_saveexec_b64 s[6:7], s[6:7]
	s_cbranch_execz .LBB0_372
	v_add_u32_e32 v60, 0xffffbf80, v194
	v_lshlrev_b32_e32 v56, 1, v60
	v_or_b32_e32 v184, 1, v56
	v_mov_b32_e32 v57, v185
	v_lshlrev_b64 v[58:59], 12, v[184:185]
	v_lshlrev_b64 v[56:57], 12, v[56:57]
	s_movk_i32 s8, 0x3400
	v_lshl_add_u64 v[58:59], v[178:179], 0, v[58:59]
	v_lshl_add_u64 v[72:73], v[178:179], 0, v[56:57]
	v_mad_u64_u32 v[104:105], s[8:9], v60, s8, v[180:181]
	global_load_dwordx4 v[60:63], v[58:59], off offset:16 nt
	s_nop 0
	global_load_dwordx4 v[56:59], v[58:59], off nt
	s_nop 0
	global_load_dwordx4 v[76:79], v[72:73], off offset:16 nt
	s_nop 0
	global_load_dwordx4 v[72:75], v[72:73], off nt
	s_nop 0
	global_load_dwordx4 v[108:111], v[104:105], off offset:16 nt
	s_nop 0
	global_load_dwordx4 v[104:107], v[104:105], off nt
	s_waitcnt vmcnt(7)
	v_mov_b32_e32 v127, 0
	v_mov_b32_e32 v126, 0
	v_mov_b32_e32 v125, 0
	v_mov_b32_e32 v124, 0
	s_waitcnt vmcnt(6)
	v_mov_b32_e32 v123, 0
	v_mov_b32_e32 v122, 0
	v_mov_b32_e32 v121, 0
	v_mov_b32_e32 v120, 0
	v_mov_b32_e32 v131, 0
	v_mov_b32_e32 v130, 0
	v_mov_b32_e32 v129, 0
	v_mov_b32_e32 v128, 0
